# hyena epilogue 1 hand-written too (batched unaligned row loads, silu/skip math unchanged)
# speedup vs baseline: 1.0253x; 1.0096x over previous
; #define MFMA(a, b, c) __builtin_amdgcn_mfma_f32_32x32x16_bf16((a), (b), (c), 0, 0, 0)
; DI void hy_conv(f32x16 (&acc)[4], const u16* abase, const u16* U, const u16* Zrow, int a0, int li, int g) {
;     ...
;   for (; d <= a0 + 15; ++d) {
;     hy_bfrag(bf, U, Zrow, a0, li, g, d);
;     u32x4 Wn[8];
;     const int dn = (d < a0 + 15) ? d + 1 : d;
; #pragma unroll
;     for (int x = 0; x < 8; ++x) Wn[x] = hy_afrag(abase, 8 * dn + x - 1);
; #pragma unroll
;     for (int kc = 0; kc < 8; ++kc)
; #pragma unroll
;       for (int I = 0; I < 4; ++I) acc[I] = MFMA(__builtin_bit_cast(bf16x8, W[2 * I - kc + 7]), bf[kc], acc[I]);
; #pragma unroll
;     for (int x = 0; x < 6; ++x) W[x] = W[x + 8];
; #pragma unroll
;     for (int x = 0; x < 8; ++x) W[x + 6] = Wn[x];
;   }
.LBB0_457:
	s_waitcnt lgkmcnt(8)
	v_mov_b32_e32 v83, v95
	v_mov_b32_e32 v82, v94
	v_mov_b32_e32 v81, v93
	v_mov_b32_e32 v80, v92
	s_waitcnt lgkmcnt(4)
	v_mov_b32_e32 v87, v107
	v_mov_b32_e32 v86, v106
	v_mov_b32_e32 v85, v105
	v_mov_b32_e32 v84, v104
	s_waitcnt lgkmcnt(0)
	v_mov_b32_e32 v91, v115
	v_mov_b32_e32 v90, v114
	v_mov_b32_e32 v89, v113
	v_mov_b32_e32 v88, v112
	s_add_i32 s8, 0, 0x18880
	v_cmp_gt_u32_e32 vcc, 64, v188
	v_mov_b32_e32 v92, s8
	v_mov_b32_e32 v71, v103
	v_cndmask_b32_e32 v92, v92, v185, vcc
	v_add_u32_e32 v92, v92, v222
	ds_read_b128 v[190:193], v92
	ds_read_b128 v[180:183], v92 offset:32
	ds_read_b128 v[176:179], v92 offset:64
	ds_read_b128 v[172:175], v92 offset:96
	ds_read_b128 v[168:171], v92 offset:128
	ds_read_b128 v[164:167], v92 offset:160
	ds_read_b128 v[160:163], v92 offset:192
	ds_read_b128 v[156:159], v92 offset:224
	s_waitcnt lgkmcnt(7)
	v_mfma_f32_32x32x16_bf16 v[48:63], v[124:127], v[190:193], v[48:63]
	v_mov_b32_e32 v70, v102
	v_mov_b32_e32 v69, v101
	v_mov_b32_e32 v68, v100
	v_mov_b32_e32 v79, v99
	v_mov_b32_e32 v78, v98
	v_mov_b32_e32 v77, v97
	v_mov_b32_e32 v76, v96
	v_mfma_f32_32x32x16_bf16 v[32:47], v[80:83], v[190:193], v[32:47]
	v_mov_b32_e32 v75, v111
	v_mov_b32_e32 v74, v110
	v_mov_b32_e32 v73, v109
	v_mov_b32_e32 v72, v108
	v_cmp_lt_i32_e32 vcc, v228, v226
	v_add_u32_e32 v194, 1, v228
	v_add_u32_e32 v185, 0xfffffef0, v185
	v_mfma_f32_32x32x16_bf16 v[16:31], v[84:87], v[190:193], v[16:31]
	v_cndmask_b32_e32 v92, v228, v194, vcc
	v_lshlrev_b32_e32 v112, 8, v92
	v_sub_u32_e32 v92, v225, v112
	ds_read2_b32 v[116:117], v92 offset0:8 offset1:9
	ds_read2_b32 v[118:119], v92 offset0:10 offset1:11
	ds_read2_b32 v[144:145], v92 offset1:1
	ds_read2_b32 v[146:147], v92 offset0:2 offset1:3
	v_xad_u32 v92, v112, s93, v225
	v_xad_u32 v94, v112, s92, v225
	v_xad_u32 v98, v112, s60, v225
	v_mfma_f32_32x32x16_bf16 v[0:15], v[88:91], v[190:193], v[0:15]
	v_xad_u32 v106, v112, s54, v225
	v_xad_u32 v110, v112, s55, v225
	v_xad_u32 v114, v112, s66, v225
	ds_read2_b32 v[100:101], v92 offset1:1
	ds_read2_b32 v[102:103], v92 offset0:2 offset1:3
	ds_read2_b32 v[92:93], v94 offset1:1
	ds_read2_b32 v[94:95], v94 offset0:2 offset1:3
	ds_read2_b32 v[96:97], v98 offset1:1
	ds_read2_b32 v[98:99], v98 offset0:2 offset1:3
	ds_read2_b32 v[104:105], v106 offset1:1
	ds_read2_b32 v[106:107], v106 offset0:2 offset1:3
	s_waitcnt lgkmcnt(14)
	v_mfma_f32_32x32x16_bf16 v[48:63], v[120:123], v[180:183], v[48:63]
	ds_read2_b32 v[108:109], v110 offset1:1
	ds_read2_b32 v[110:111], v110 offset0:2 offset1:3
	ds_read2_b32 v[112:113], v114 offset1:1
	ds_read2_b32 v[114:115], v114 offset0:2 offset1:3
	v_cmp_eq_u32_e32 vcc, v228, v227
	v_add_u32_e32 v188, -1, v188
	s_or_b64 s[6:7], vcc, s[6:7]
	v_mov_b32_e32 v228, v194
	v_mfma_f32_32x32x16_bf16 v[32:47], v[68:71], v[180:183], v[32:47]
	v_mfma_f32_32x32x16_bf16 v[16:31], v[76:79], v[180:183], v[16:31]
	v_mfma_f32_32x32x16_bf16 v[0:15], v[72:75], v[180:183], v[0:15]
	v_mfma_f32_32x32x16_bf16 v[48:63], v[132:135], v[176:179], v[48:63]
	v_mfma_f32_32x32x16_bf16 v[32:47], v[124:127], v[176:179], v[32:47]
	v_mfma_f32_32x32x16_bf16 v[16:31], v[80:83], v[176:179], v[16:31]
	v_mfma_f32_32x32x16_bf16 v[0:15], v[84:87], v[176:179], v[0:15]
	v_mfma_f32_32x32x16_bf16 v[48:63], v[128:131], v[172:175], v[48:63]
	v_mfma_f32_32x32x16_bf16 v[32:47], v[120:123], v[172:175], v[32:47]
	v_mfma_f32_32x32x16_bf16 v[16:31], v[68:71], v[172:175], v[16:31]
	v_mfma_f32_32x32x16_bf16 v[0:15], v[76:79], v[172:175], v[0:15]
	v_mfma_f32_32x32x16_bf16 v[48:63], v[136:139], v[168:171], v[48:63]
	v_mfma_f32_32x32x16_bf16 v[32:47], v[132:135], v[168:171], v[32:47]
	v_mfma_f32_32x32x16_bf16 v[16:31], v[124:127], v[168:171], v[16:31]
	v_mfma_f32_32x32x16_bf16 v[0:15], v[80:83], v[168:171], v[0:15]
	v_mfma_f32_32x32x16_bf16 v[48:63], v[140:143], v[164:167], v[48:63]
	v_mfma_f32_32x32x16_bf16 v[32:47], v[128:131], v[164:167], v[32:47]
	v_mfma_f32_32x32x16_bf16 v[16:31], v[120:123], v[164:167], v[16:31]
	v_mfma_f32_32x32x16_bf16 v[0:15], v[68:71], v[164:167], v[0:15]
	s_waitcnt lgkmcnt(14)
	v_mfma_f32_32x32x16_bf16 v[48:63], v[148:151], v[160:163], v[48:63]
	v_mov_b32_e32 v148, v80
	v_mov_b32_e32 v149, v81
	v_mov_b32_e32 v150, v82
	v_mov_b32_e32 v151, v83
	v_mfma_f32_32x32x16_bf16 v[32:47], v[136:139], v[160:163], v[32:47]
	v_mov_b32_e32 v136, v84
	v_mov_b32_e32 v137, v85
	v_mov_b32_e32 v138, v86
	v_mov_b32_e32 v139, v87
	v_mfma_f32_32x32x16_bf16 v[16:31], v[132:135], v[160:163], v[16:31]
	v_mov_b32_e32 v132, v88
	v_mov_b32_e32 v133, v89
	v_mov_b32_e32 v134, v90
	v_mov_b32_e32 v135, v91
	v_mfma_f32_32x32x16_bf16 v[0:15], v[124:127], v[160:163], v[0:15]
	s_waitcnt lgkmcnt(13)
	v_mov_b32_e32 v124, v144
	v_mov_b32_e32 v125, v145
	s_waitcnt lgkmcnt(12)
	v_mov_b32_e32 v126, v146
	v_mov_b32_e32 v127, v147
	v_mfma_f32_32x32x16_bf16 v[48:63], v[152:155], v[156:159], v[48:63]
	v_mov_b32_e32 v152, v68
	v_mov_b32_e32 v153, v69
	v_mov_b32_e32 v154, v70
	v_mov_b32_e32 v155, v71
	v_mfma_f32_32x32x16_bf16 v[32:47], v[140:143], v[156:159], v[32:47]
	v_mov_b32_e32 v140, v76
	v_mov_b32_e32 v141, v77
	v_mov_b32_e32 v142, v78
	v_mov_b32_e32 v143, v79
	v_mfma_f32_32x32x16_bf16 v[16:31], v[128:131], v[156:159], v[16:31]
	v_mov_b32_e32 v128, v72
	v_mov_b32_e32 v129, v73
	v_mov_b32_e32 v130, v74
	v_mov_b32_e32 v131, v75
	v_mfma_f32_32x32x16_bf16 v[0:15], v[120:123], v[156:159], v[0:15]
	v_mov_b32_e32 v120, v116
	v_mov_b32_e32 v121, v117
	v_mov_b32_e32 v122, v118
	v_mov_b32_e32 v123, v119
	s_andn2_b64 exec, exec, s[6:7]
	s_cbranch_execnz .LBB0_457
; #define MFMA(a, b, c) __builtin_amdgcn_mfma_f32_32x32x16_bf16((a), (b), (c), 0, 0, 0)
; DI void hy_conv(f32x16 (&acc)[4], const u16* abase, const u16* U, const u16* Zrow, int a0, int li, int g) {
;     ...
;   for (; d <= a0 + 15; ++d) {
;     hy_bfrag(bf, U, Zrow, a0, li, g, d);
;     u32x4 Wn[8];
;     const int dn = (d < a0 + 15) ? d + 1 : d;
; #pragma unroll
;     for (int x = 0; x < 8; ++x) Wn[x] = hy_afrag(abase, 8 * dn + x - 1);
; #pragma unroll
;     for (int kc = 0; kc < 8; ++kc)
; #pragma unroll
;       for (int I = 0; I < 4; ++I) acc[I] = MFMA(__builtin_bit_cast(bf16x8, W[2 * I - kc + 7]), bf[kc], acc[I]);
; #pragma unroll
;     for (int x = 0; x < 6; ++x) W[x] = W[x + 8];
; #pragma unroll
;     for (int x = 0; x < 8; ++x) W[x + 6] = Wn[x];
;   }
; DI void hyena_item(const P& p, int l, int c, char* smem) {
;     ...
;   if (cwv) {
;     const float d1 = p.fbias[(size_t)(l * 2 + 1) * 512 + c];
;     const float x0 = cw[1024 + c], x1 = cw[1536 + 1024 + c], x2 = cw[3072 + 1024 + c], xb = cbias[1024 + c];
;     const u16* rowx = p.hyT + (size_t)(1024 + c) * HYP + bt * SEQ;
;     const u16* rowg = p.hyT + (size_t)(1536 + c) * HYP + bt * SEQ;
;     u16* dst = p.YhT + (size_t)c * HYP + bt * SEQ;
; #pragma unroll
;     for (int I = 0; I < 4; ++I)
; #pragma unroll
;       for (int rq = 0; rq < 4; ++rq) {
;         const int bq = 32 * I + 8 * rq + 4 * g;
;         const int t4 = 128 * a + bq;
	s_or_b64 exec, exec, s[6:7]
	v_add_u32_e32 v120, -15, v223
	v_add_u32_e32 v121, v224, v120
	v_mov_b32_e32 v122, s69
	v_mad_i32_i24 v121, v121, s97, v122
	v_mov_b32_e32 v122, s8
	v_cmp_gt_u32_e32 vcc, 64, v120
	v_readlane_b32 s6, v248, 24
	s_add_i32 s6, s72, s6
	v_cndmask_b32_e32 v120, v122, v121, vcc
	v_add_u32_e32 v124, v120, v222
	ds_read_b128 v[120:123], v124
	s_waitcnt lgkmcnt(0)
	v_mfma_f32_32x32x16_bf16 v[48:63], v[144:147], v[120:123], v[48:63]
	s_mov_b32 s7, s57
	s_lshl_b64 s[6:7], s[6:7], 2
	s_add_u32 s6, s20, s6
	s_addc_u32 s7, s21, s7
	s_or_b32 s8, s72, 0x400
	s_mov_b32 s9, s57
	s_lshl_b64 s[14:15], s[8:9], 2
	v_mfma_f32_32x32x16_bf16 v[32:47], v[92:95], v[120:123], v[32:47]
	s_add_u32 s76, s28, s14
	s_addc_u32 s77, s29, s15
	v_readlane_b32 s9, v248, 28
	s_add_u32 s14, s9, s14
	v_readlane_b32 s9, v248, 29
	s_addc_u32 s15, s9, s15
	v_mov_b32_e32 v185, v189
	v_mfma_f32_32x32x16_bf16 v[16:31], v[104:107], v[120:123], v[16:31]
	v_lshlrev_b32_e32 v188, 1, v233
	v_cmp_ne_u32_e32 vcc, 0, v233
	v_mfma_f32_32x32x16_bf16 v[0:15], v[112:115], v[120:123], v[0:15]
	ds_read_b128 v[112:115], v124 offset:32
	s_waitcnt lgkmcnt(0)
	v_mfma_f32_32x32x16_bf16 v[48:63], v[116:119], v[112:115], v[48:63]
	v_mfma_f32_32x32x16_bf16 v[32:47], v[100:103], v[112:115], v[32:47]
	v_mfma_f32_32x32x16_bf16 v[16:31], v[96:99], v[112:115], v[16:31]
	v_mfma_f32_32x32x16_bf16 v[0:15], v[108:111], v[112:115], v[0:15]
	ds_read_b128 v[108:111], v124 offset:64
	s_waitcnt lgkmcnt(0)
	v_mfma_f32_32x32x16_bf16 v[48:63], v[88:91], v[108:111], v[48:63]
	v_mfma_f32_32x32x16_bf16 v[32:47], v[144:147], v[108:111], v[32:47]
	v_mfma_f32_32x32x16_bf16 v[16:31], v[92:95], v[108:111], v[16:31]
	v_mfma_f32_32x32x16_bf16 v[0:15], v[104:107], v[108:111], v[0:15]
	ds_read_b128 v[104:107], v124 offset:96
	s_waitcnt lgkmcnt(0)
	v_mfma_f32_32x32x16_bf16 v[48:63], v[72:75], v[104:107], v[48:63]
	v_mfma_f32_32x32x16_bf16 v[32:47], v[116:119], v[104:107], v[32:47]
	v_mfma_f32_32x32x16_bf16 v[16:31], v[100:103], v[104:107], v[16:31]
	v_mfma_f32_32x32x16_bf16 v[0:15], v[96:99], v[104:107], v[0:15]
	ds_read_b128 v[96:99], v124 offset:128
	s_waitcnt lgkmcnt(0)
	v_mfma_f32_32x32x16_bf16 v[48:63], v[84:87], v[96:99], v[48:63]
	v_mfma_f32_32x32x16_bf16 v[32:47], v[88:91], v[96:99], v[32:47]
	v_mfma_f32_32x32x16_bf16 v[16:31], v[144:147], v[96:99], v[16:31]
	v_mfma_f32_32x32x16_bf16 v[0:15], v[92:95], v[96:99], v[0:15]
	ds_read_b128 v[92:95], v124 offset:160
	s_waitcnt lgkmcnt(0)
	v_mfma_f32_32x32x16_bf16 v[48:63], v[76:79], v[92:95], v[48:63]
	v_mfma_f32_32x32x16_bf16 v[32:47], v[72:75], v[92:95], v[32:47]
	v_mfma_f32_32x32x16_bf16 v[16:31], v[116:119], v[92:95], v[16:31]
	v_mfma_f32_32x32x16_bf16 v[0:15], v[100:103], v[92:95], v[0:15]
	ds_read_b128 v[92:95], v124 offset:192
	s_waitcnt lgkmcnt(0)
	v_mfma_f32_32x32x16_bf16 v[48:63], v[80:83], v[92:95], v[48:63]
	v_mfma_f32_32x32x16_bf16 v[32:47], v[84:87], v[92:95], v[32:47]
	v_mfma_f32_32x32x16_bf16 v[16:31], v[88:91], v[92:95], v[16:31]
	ds_read_b128 v[86:89], v124 offset:224
	global_load_dword v82, v204, s[74:75] offset:2048
	global_load_dword v80, v207, s[74:75]
	s_waitcnt lgkmcnt(0)
	v_mfma_f32_32x32x16_bf16 v[48:63], v[68:71], v[86:89], v[48:63]
	global_load_dword v68, v189, s[6:7] offset:2048
	global_load_dword v83, v189, s[76:77]
	global_load_dword v70, v189, s[14:15]
	s_mul_i32 s6, s8, 0x8080
	s_mul_hi_u32 s7, s8, 0x8080
	s_add_u32 s6, s36, s6
	s_addc_u32 s7, s37, s7
	v_mfma_f32_32x32x16_bf16 v[16:31], v[72:75], v[86:89], v[16:31]
	v_lshl_add_u64 v[74:75], s[6:7], 0, v[184:185]
	v_lshl_add_u64 v[84:85], v[74:75], 0, v[188:189]
	v_mov_b32_e32 v73, 0
	v_mfma_f32_32x32x16_bf16 v[32:47], v[76:79], v[86:89], v[32:47]
	global_load_dwordx2 v[78:79], v[84:85], off
	v_mov_b32_e32 v77, 0
	v_mfma_f32_32x32x16_bf16 v[0:15], v[144:147], v[92:95], v[0:15]
	v_mfma_f32_32x32x16_bf16 v[0:15], v[116:119], v[86:89], v[0:15]
	s_waitcnt vmcnt(0)
	s_or_b32 s98, s72, 0x400
	s_mul_hi_u32 s99, s98, 0x8080
	s_mul_i32 s98, s98, 0x8080
	s_add_u32 s98, s36, s98
	s_addc_u32 s99, s37, s99
	s_add_u32 s98, s98, -4
	s_addc_u32 s99, s99, -1
	s_or_b32 s100, s72, 0x600
	s_mul_hi_u32 s101, s100, 0x8080
	s_mul_i32 s100, s100, 0x8080
	s_add_u32 s100, s36, s100
	s_addc_u32 s101, s37, s101
	s_add_u32 s6, s48, s96
	s_addc_u32 s7, s49, s73
	v_lshl_add_u32 v234, v233, 1, v184
	global_load_dwordx4 v[88:91], v234, s[98:99] offset:0
	global_load_dwordx2 v[92:93], v234, s[100:101] offset:0
	global_load_dwordx4 v[94:97], v234, s[98:99] offset:16
	global_load_dwordx2 v[98:99], v234, s[100:101] offset:16
	global_load_dwordx4 v[100:103], v234, s[98:99] offset:32
	global_load_dwordx2 v[104:105], v234, s[100:101] offset:32
	global_load_dwordx4 v[106:109], v234, s[98:99] offset:48
	global_load_dwordx2 v[110:111], v234, s[100:101] offset:48
	global_load_dwordx4 v[112:115], v234, s[98:99] offset:64
	global_load_dwordx2 v[116:117], v234, s[100:101] offset:64
	global_load_dwordx4 v[118:121], v234, s[98:99] offset:80
	global_load_dwordx2 v[122:123], v234, s[100:101] offset:80
	global_load_dwordx4 v[124:127], v234, s[98:99] offset:96
	global_load_dwordx2 v[128:129], v234, s[100:101] offset:96
	global_load_dwordx4 v[130:133], v234, s[98:99] offset:112
	global_load_dwordx2 v[134:135], v234, s[100:101] offset:112
	v_add_f32_e32 v238, v64, v65
	v_add_f32_e32 v238, v238, v66
	v_add_f32_e32 v238, v238, v67
	v_div_scale_f32 v169, s[8:9], v238, v238, 1.0
	v_rcp_f32_e32 v170, v169
	s_nop 0
	v_fma_f32 v171, -v169, v170, 1.0
	v_fmac_f32_e32 v170, v171, v170
	v_div_scale_f32 v171, vcc, 1.0, v238, 1.0
	v_mul_f32_e32 v236, v171, v170
	v_fma_f32 v237, -v169, v236, v171
	v_fmac_f32_e32 v236, v237, v170
	v_fma_f32 v169, -v169, v236, v171
	v_div_fmas_f32 v169, v169, v170, v236
	v_div_fixup_f32 v238, v169, v238, 1.0
	v_lshl_or_b32 v235, v230, 6, v231
	v_mul_u32_u24_e32 v235, 0x110, v235
	v_lshlrev_b32_e32 v236, 1, v186
	v_add3_u32 v235, s69, v235, v236
	s_waitcnt vmcnt(8)
; DI float bflo(unsigned v) { return __uint_as_float(v << 16); }
; DI float bfhi(unsigned v) { return __uint_as_float(v & 0xffff0000u); }
; DI float siluf(float x) { return x * __builtin_amdgcn_rcpf(1.f + __expf(-x)); }
; DI void hyena_item(const P& p, int l, int c, char* smem) {
;     ...
; #pragma unroll
;     for (int I = 0; I < 4; ++I)
; #pragma unroll
;       for (int rq = 0; rq < 4; ++rq) {
;         const int bq = 32 * I + 8 * rq + 4 * g;
;         const int t4 = 128 * a + bq;
;         float px[4];
;         sconv4(rowx, t4, x0, x1, x2, xb, px);
;         const uint2 zv = *(const uint2*)(U + (bt * 64 + a) * 136 + bq);
;         const uint2 gv = *(const uint2*)(rowg + t4);
;         const float z1[4] = {bflo(zv.x), bfhi(zv.x), bflo(zv.y), bfhi(zv.y)};
;         const float gt[4] = {bflo(gv.x), bfhi(gv.x), bflo(gv.y), bfhi(gv.y)};
;         float yy[4];
; #pragma unroll
;         for (int j = 0; j < 4; ++j) yy[j] = px[j] * (acc[I][4 * rq + j] * invn1 + z1[j] * d1) * siluf(gt[j]);
;         uint2 ov; ov.x = pack2(yy[0], yy[1]); ov.y = pack2(yy[2], yy[3]);
;         *(uint2*)(dst + t4) = ov;
;       }
	ds_read_b64 v[160:161], v235 offset:0
	ds_read_b64 v[162:163], v235 offset:16
	ds_read_b64 v[164:165], v235 offset:32
	ds_read_b64 v[166:167], v235 offset:48
	v_cmp_ne_u32_e32 vcc, 0, v233
	s_nop 1
	v_and_b32_e32 v168, 0xffff0000, v88
	v_cndmask_b32_e32 v168, 0, v168, vcc
	v_lshlrev_b32_e32 v169, 16, v89
	v_and_b32_e32 v170, 0xffff0000, v89
	v_lshlrev_b32_e32 v171, 16, v90
	v_and_b32_e32 v172, 0xffff0000, v90
	v_lshlrev_b32_e32 v173, 16, v91
	v_mul_f32_e32 v178, v83, v168
	v_fmac_f32_e32 v178, v82, v169
	v_fmac_f32_e32 v178, v80, v170
	v_add_f32_e32 v178, v70, v178
	v_mul_f32_e32 v179, v83, v169
	v_fmac_f32_e32 v179, v82, v170
	v_fmac_f32_e32 v179, v80, v171
	v_add_f32_e32 v179, v70, v179
	v_mul_f32_e32 v180, v83, v170
	v_fmac_f32_e32 v180, v82, v171
	v_fmac_f32_e32 v180, v80, v172
	v_add_f32_e32 v180, v70, v180
	v_mul_f32_e32 v181, v83, v171
	v_fmac_f32_e32 v181, v82, v172
	v_fmac_f32_e32 v181, v80, v173
	v_add_f32_e32 v181, v70, v181
	s_waitcnt lgkmcnt(0)
	v_lshlrev_b32_e32 v174, 16, v160
	v_and_b32_e32 v175, 0xffff0000, v160
	v_lshlrev_b32_e32 v176, 16, v161
	v_and_b32_e32 v177, 0xffff0000, v161
	v_mul_f32_e32 v174, v68, v174
	v_mul_f32_e32 v175, v68, v175
	v_mul_f32_e32 v176, v68, v176
	v_mul_f32_e32 v177, v68, v177
	v_fmac_f32_e32 v174, v238, v48
	v_fmac_f32_e32 v175, v238, v49
	v_fmac_f32_e32 v176, v238, v50
	v_fmac_f32_e32 v177, v238, v51
	v_mul_f32_e32 v174, v178, v174
	v_mul_f32_e32 v175, v179, v175
	v_mul_f32_e32 v176, v180, v176
	v_mul_f32_e32 v177, v181, v177
	v_lshlrev_b32_e32 v168, 16, v92
	v_and_b32_e32 v169, 0xffff0000, v92
	v_lshlrev_b32_e32 v170, 16, v93
	v_and_b32_e32 v171, 0xffff0000, v93
	v_mul_f32_e32 v178, 0xbfb8aa3b, v168
	v_mul_f32_e32 v179, 0xbfb8aa3b, v169
	v_mul_f32_e32 v180, 0xbfb8aa3b, v170
	v_mul_f32_e32 v181, 0xbfb8aa3b, v171
	v_exp_f32_e32 v178, v178
	v_exp_f32_e32 v179, v179
	v_exp_f32_e32 v180, v180
	v_exp_f32_e32 v181, v181
	v_add_f32_e32 v178, 1.0, v178
	v_add_f32_e32 v179, 1.0, v179
	v_add_f32_e32 v180, 1.0, v180
	v_add_f32_e32 v181, 1.0, v181
	v_rcp_f32_e32 v178, v178
	v_rcp_f32_e32 v179, v179
	v_rcp_f32_e32 v180, v180
	v_rcp_f32_e32 v181, v181
	v_mul_f32_e32 v178, v178, v168
	v_mul_f32_e32 v179, v179, v169
	v_mul_f32_e32 v180, v180, v170
	v_mul_f32_e32 v181, v181, v171
	v_mul_f32_e32 v174, v174, v178
	v_mul_f32_e32 v175, v175, v179
	v_mul_f32_e32 v176, v176, v180
	v_mul_f32_e32 v177, v177, v181
	v_cvt_pk_bf16_f32 v182, v174, v175
	v_cvt_pk_bf16_f32 v183, v176, v177
	global_store_dwordx2 v234, v[182:183], s[6:7] offset:0
	v_and_b32_e32 v168, 0xffff0000, v94
	v_lshlrev_b32_e32 v169, 16, v95
	v_and_b32_e32 v170, 0xffff0000, v95
	v_lshlrev_b32_e32 v171, 16, v96
	v_and_b32_e32 v172, 0xffff0000, v96
	v_lshlrev_b32_e32 v173, 16, v97
	v_mul_f32_e32 v178, v83, v168
	v_fmac_f32_e32 v178, v82, v169
	v_fmac_f32_e32 v178, v80, v170
	v_add_f32_e32 v178, v70, v178
	v_mul_f32_e32 v179, v83, v169
	v_fmac_f32_e32 v179, v82, v170
	v_fmac_f32_e32 v179, v80, v171
	v_add_f32_e32 v179, v70, v179
	v_mul_f32_e32 v180, v83, v170
	v_fmac_f32_e32 v180, v82, v171
	v_fmac_f32_e32 v180, v80, v172
	v_add_f32_e32 v180, v70, v180
	v_mul_f32_e32 v181, v83, v171
	v_fmac_f32_e32 v181, v82, v172
	v_fmac_f32_e32 v181, v80, v173
	v_add_f32_e32 v181, v70, v181
	v_lshlrev_b32_e32 v174, 16, v162
	v_and_b32_e32 v175, 0xffff0000, v162
	v_lshlrev_b32_e32 v176, 16, v163
	v_and_b32_e32 v177, 0xffff0000, v163
	v_mul_f32_e32 v174, v68, v174
	v_mul_f32_e32 v175, v68, v175
	v_mul_f32_e32 v176, v68, v176
	v_mul_f32_e32 v177, v68, v177
	v_fmac_f32_e32 v174, v238, v52
	v_fmac_f32_e32 v175, v238, v53
	v_fmac_f32_e32 v176, v238, v54
	v_fmac_f32_e32 v177, v238, v55
	v_mul_f32_e32 v174, v178, v174
	v_mul_f32_e32 v175, v179, v175
	v_mul_f32_e32 v176, v180, v176
	v_mul_f32_e32 v177, v181, v177
	v_lshlrev_b32_e32 v168, 16, v98
	v_and_b32_e32 v169, 0xffff0000, v98
	v_lshlrev_b32_e32 v170, 16, v99
	v_and_b32_e32 v171, 0xffff0000, v99
	v_mul_f32_e32 v178, 0xbfb8aa3b, v168
	v_mul_f32_e32 v179, 0xbfb8aa3b, v169
	v_mul_f32_e32 v180, 0xbfb8aa3b, v170
	v_mul_f32_e32 v181, 0xbfb8aa3b, v171
	v_exp_f32_e32 v178, v178
	v_exp_f32_e32 v179, v179
	v_exp_f32_e32 v180, v180
	v_exp_f32_e32 v181, v181
	v_add_f32_e32 v178, 1.0, v178
	v_add_f32_e32 v179, 1.0, v179
	v_add_f32_e32 v180, 1.0, v180
	v_add_f32_e32 v181, 1.0, v181
	v_rcp_f32_e32 v178, v178
	v_rcp_f32_e32 v179, v179
	v_rcp_f32_e32 v180, v180
	v_rcp_f32_e32 v181, v181
	v_mul_f32_e32 v178, v178, v168
	v_mul_f32_e32 v179, v179, v169
	v_mul_f32_e32 v180, v180, v170
	v_mul_f32_e32 v181, v181, v171
	v_mul_f32_e32 v174, v174, v178
	v_mul_f32_e32 v175, v175, v179
	v_mul_f32_e32 v176, v176, v180
	v_mul_f32_e32 v177, v177, v181
	v_cvt_pk_bf16_f32 v182, v174, v175
	v_cvt_pk_bf16_f32 v183, v176, v177
	global_store_dwordx2 v234, v[182:183], s[6:7] offset:16
	v_and_b32_e32 v168, 0xffff0000, v100
	v_lshlrev_b32_e32 v169, 16, v101
	v_and_b32_e32 v170, 0xffff0000, v101
	v_lshlrev_b32_e32 v171, 16, v102
	v_and_b32_e32 v172, 0xffff0000, v102
	v_lshlrev_b32_e32 v173, 16, v103
	v_mul_f32_e32 v178, v83, v168
	v_fmac_f32_e32 v178, v82, v169
	v_fmac_f32_e32 v178, v80, v170
	v_add_f32_e32 v178, v70, v178
	v_mul_f32_e32 v179, v83, v169
	v_fmac_f32_e32 v179, v82, v170
	v_fmac_f32_e32 v179, v80, v171
	v_add_f32_e32 v179, v70, v179
	v_mul_f32_e32 v180, v83, v170
	v_fmac_f32_e32 v180, v82, v171
	v_fmac_f32_e32 v180, v80, v172
	v_add_f32_e32 v180, v70, v180
	v_mul_f32_e32 v181, v83, v171
	v_fmac_f32_e32 v181, v82, v172
	v_fmac_f32_e32 v181, v80, v173
	v_add_f32_e32 v181, v70, v181
	v_lshlrev_b32_e32 v174, 16, v164
	v_and_b32_e32 v175, 0xffff0000, v164
	v_lshlrev_b32_e32 v176, 16, v165
	v_and_b32_e32 v177, 0xffff0000, v165
	v_mul_f32_e32 v174, v68, v174
; DI float bflo(unsigned v) { return __uint_as_float(v << 16); }
; DI float bfhi(unsigned v) { return __uint_as_float(v & 0xffff0000u); }
; DI float siluf(float x) { return x * __builtin_amdgcn_rcpf(1.f + __expf(-x)); }
; DI void hyena_item(const P& p, int l, int c, char* smem) {
;     ...
; #pragma unroll
;     for (int I = 0; I < 4; ++I)
; #pragma unroll
;       for (int rq = 0; rq < 4; ++rq) {
;         const int bq = 32 * I + 8 * rq + 4 * g;
;         const int t4 = 128 * a + bq;
;         float px[4];
;         sconv4(rowx, t4, x0, x1, x2, xb, px);
;         const uint2 zv = *(const uint2*)(U + (bt * 64 + a) * 136 + bq);
;         const uint2 gv = *(const uint2*)(rowg + t4);
;         const float z1[4] = {bflo(zv.x), bfhi(zv.x), bflo(zv.y), bfhi(zv.y)};
;         const float gt[4] = {bflo(gv.x), bfhi(gv.x), bflo(gv.y), bfhi(gv.y)};
;         float yy[4];
; #pragma unroll
;         for (int j = 0; j < 4; ++j) yy[j] = px[j] * (acc[I][4 * rq + j] * invn1 + z1[j] * d1) * siluf(gt[j]);
;         uint2 ov; ov.x = pack2(yy[0], yy[1]); ov.y = pack2(yy[2], yy[3]);
;         *(uint2*)(dst + t4) = ov;
;       }
	v_mul_f32_e32 v175, v68, v175
	v_mul_f32_e32 v176, v68, v176
	v_mul_f32_e32 v177, v68, v177
	v_fmac_f32_e32 v174, v238, v56
	v_fmac_f32_e32 v175, v238, v57
	v_fmac_f32_e32 v176, v238, v58
	v_fmac_f32_e32 v177, v238, v59
	v_mul_f32_e32 v174, v178, v174
	v_mul_f32_e32 v175, v179, v175
	v_mul_f32_e32 v176, v180, v176
	v_mul_f32_e32 v177, v181, v177
	v_lshlrev_b32_e32 v168, 16, v104
	v_and_b32_e32 v169, 0xffff0000, v104
	v_lshlrev_b32_e32 v170, 16, v105
	v_and_b32_e32 v171, 0xffff0000, v105
	v_mul_f32_e32 v178, 0xbfb8aa3b, v168
	v_mul_f32_e32 v179, 0xbfb8aa3b, v169
	v_mul_f32_e32 v180, 0xbfb8aa3b, v170
	v_mul_f32_e32 v181, 0xbfb8aa3b, v171
	v_exp_f32_e32 v178, v178
	v_exp_f32_e32 v179, v179
	v_exp_f32_e32 v180, v180
	v_exp_f32_e32 v181, v181
	v_add_f32_e32 v178, 1.0, v178
	v_add_f32_e32 v179, 1.0, v179
	v_add_f32_e32 v180, 1.0, v180
	v_add_f32_e32 v181, 1.0, v181
	v_rcp_f32_e32 v178, v178
	v_rcp_f32_e32 v179, v179
	v_rcp_f32_e32 v180, v180
	v_rcp_f32_e32 v181, v181
	v_mul_f32_e32 v178, v178, v168
	v_mul_f32_e32 v179, v179, v169
	v_mul_f32_e32 v180, v180, v170
	v_mul_f32_e32 v181, v181, v171
	v_mul_f32_e32 v174, v174, v178
	v_mul_f32_e32 v175, v175, v179
	v_mul_f32_e32 v176, v176, v180
	v_mul_f32_e32 v177, v177, v181
	v_cvt_pk_bf16_f32 v182, v174, v175
	v_cvt_pk_bf16_f32 v183, v176, v177
	global_store_dwordx2 v234, v[182:183], s[6:7] offset:32
	v_and_b32_e32 v168, 0xffff0000, v106
	v_lshlrev_b32_e32 v169, 16, v107
	v_and_b32_e32 v170, 0xffff0000, v107
	v_lshlrev_b32_e32 v171, 16, v108
	v_and_b32_e32 v172, 0xffff0000, v108
	v_lshlrev_b32_e32 v173, 16, v109
	v_mul_f32_e32 v178, v83, v168
	v_fmac_f32_e32 v178, v82, v169
	v_fmac_f32_e32 v178, v80, v170
	v_add_f32_e32 v178, v70, v178
	v_mul_f32_e32 v179, v83, v169
	v_fmac_f32_e32 v179, v82, v170
	v_fmac_f32_e32 v179, v80, v171
	v_add_f32_e32 v179, v70, v179
	v_mul_f32_e32 v180, v83, v170
	v_fmac_f32_e32 v180, v82, v171
	v_fmac_f32_e32 v180, v80, v172
	v_add_f32_e32 v180, v70, v180
	v_mul_f32_e32 v181, v83, v171
	v_fmac_f32_e32 v181, v82, v172
	v_fmac_f32_e32 v181, v80, v173
	v_add_f32_e32 v181, v70, v181
	v_lshlrev_b32_e32 v174, 16, v166
	v_and_b32_e32 v175, 0xffff0000, v166
	v_lshlrev_b32_e32 v176, 16, v167
	v_and_b32_e32 v177, 0xffff0000, v167
	v_mul_f32_e32 v174, v68, v174
	v_mul_f32_e32 v175, v68, v175
	v_mul_f32_e32 v176, v68, v176
	v_mul_f32_e32 v177, v68, v177
	v_fmac_f32_e32 v174, v238, v60
	v_fmac_f32_e32 v175, v238, v61
	v_fmac_f32_e32 v176, v238, v62
	v_fmac_f32_e32 v177, v238, v63
	v_mul_f32_e32 v174, v178, v174
	v_mul_f32_e32 v175, v179, v175
	v_mul_f32_e32 v176, v180, v176
	v_mul_f32_e32 v177, v181, v177
	v_lshlrev_b32_e32 v168, 16, v110
	v_and_b32_e32 v169, 0xffff0000, v110
	v_lshlrev_b32_e32 v170, 16, v111
	v_and_b32_e32 v171, 0xffff0000, v111
	v_mul_f32_e32 v178, 0xbfb8aa3b, v168
	v_mul_f32_e32 v179, 0xbfb8aa3b, v169
	v_mul_f32_e32 v180, 0xbfb8aa3b, v170
	v_mul_f32_e32 v181, 0xbfb8aa3b, v171
	v_exp_f32_e32 v178, v178
	v_exp_f32_e32 v179, v179
	v_exp_f32_e32 v180, v180
	v_exp_f32_e32 v181, v181
	v_add_f32_e32 v178, 1.0, v178
	v_add_f32_e32 v179, 1.0, v179
	v_add_f32_e32 v180, 1.0, v180
	v_add_f32_e32 v181, 1.0, v181
	v_rcp_f32_e32 v178, v178
	v_rcp_f32_e32 v179, v179
	v_rcp_f32_e32 v180, v180
	v_rcp_f32_e32 v181, v181
	v_mul_f32_e32 v178, v178, v168
	v_mul_f32_e32 v179, v179, v169
	v_mul_f32_e32 v180, v180, v170
	v_mul_f32_e32 v181, v181, v171
	v_mul_f32_e32 v174, v174, v178
	v_mul_f32_e32 v175, v175, v179
	v_mul_f32_e32 v176, v176, v180
	v_mul_f32_e32 v177, v177, v181
	v_cvt_pk_bf16_f32 v182, v174, v175
	v_cvt_pk_bf16_f32 v183, v176, v177
	global_store_dwordx2 v234, v[182:183], s[6:7] offset:48
	global_load_dwordx4 v[136:139], v234, s[98:99] offset:128
	global_load_dwordx2 v[140:141], v234, s[100:101] offset:128
	global_load_dwordx4 v[142:145], v234, s[98:99] offset:144
	global_load_dwordx2 v[146:147], v234, s[100:101] offset:144
	global_load_dwordx4 v[148:151], v234, s[98:99] offset:160
	global_load_dwordx2 v[152:153], v234, s[100:101] offset:160
	global_load_dwordx4 v[154:157], v234, s[98:99] offset:176
	global_load_dwordx2 v[158:159], v234, s[100:101] offset:176
	s_waitcnt vmcnt(12)
	ds_read_b64 v[160:161], v235 offset:64
	ds_read_b64 v[162:163], v235 offset:80
	ds_read_b64 v[164:165], v235 offset:96
	ds_read_b64 v[166:167], v235 offset:112
	v_and_b32_e32 v168, 0xffff0000, v112
	v_lshlrev_b32_e32 v169, 16, v113
	v_and_b32_e32 v170, 0xffff0000, v113
	v_lshlrev_b32_e32 v171, 16, v114
	v_and_b32_e32 v172, 0xffff0000, v114
	v_lshlrev_b32_e32 v173, 16, v115
	v_mul_f32_e32 v178, v83, v168
	v_fmac_f32_e32 v178, v82, v169
	v_fmac_f32_e32 v178, v80, v170
	v_add_f32_e32 v178, v70, v178
	v_mul_f32_e32 v179, v83, v169
	v_fmac_f32_e32 v179, v82, v170
	v_fmac_f32_e32 v179, v80, v171
	v_add_f32_e32 v179, v70, v179
	v_mul_f32_e32 v180, v83, v170
	v_fmac_f32_e32 v180, v82, v171
	v_fmac_f32_e32 v180, v80, v172
	v_add_f32_e32 v180, v70, v180
	v_mul_f32_e32 v181, v83, v171
	v_fmac_f32_e32 v181, v82, v172
	v_fmac_f32_e32 v181, v80, v173
	v_add_f32_e32 v181, v70, v181
	s_waitcnt lgkmcnt(0)
; DI float bflo(unsigned v) { return __uint_as_float(v << 16); }
; DI float bfhi(unsigned v) { return __uint_as_float(v & 0xffff0000u); }
; DI float siluf(float x) { return x * __builtin_amdgcn_rcpf(1.f + __expf(-x)); }
; DI void hyena_item(const P& p, int l, int c, char* smem) {
;     ...
; #pragma unroll
;     for (int I = 0; I < 4; ++I)
; #pragma unroll
;       for (int rq = 0; rq < 4; ++rq) {
;         const int bq = 32 * I + 8 * rq + 4 * g;
;         const int t4 = 128 * a + bq;
;         float px[4];
;         sconv4(rowx, t4, x0, x1, x2, xb, px);
;         const uint2 zv = *(const uint2*)(U + (bt * 64 + a) * 136 + bq);
;         const uint2 gv = *(const uint2*)(rowg + t4);
;         const float z1[4] = {bflo(zv.x), bfhi(zv.x), bflo(zv.y), bfhi(zv.y)};
;         const float gt[4] = {bflo(gv.x), bfhi(gv.x), bflo(gv.y), bfhi(gv.y)};
;         float yy[4];
; #pragma unroll
;         for (int j = 0; j < 4; ++j) yy[j] = px[j] * (acc[I][4 * rq + j] * invn1 + z1[j] * d1) * siluf(gt[j]);
;         uint2 ov; ov.x = pack2(yy[0], yy[1]); ov.y = pack2(yy[2], yy[3]);
;         *(uint2*)(dst + t4) = ov;
;       }
	v_lshlrev_b32_e32 v174, 16, v160
	v_and_b32_e32 v175, 0xffff0000, v160
	v_lshlrev_b32_e32 v176, 16, v161
	v_and_b32_e32 v177, 0xffff0000, v161
	v_mul_f32_e32 v174, v68, v174
	v_mul_f32_e32 v175, v68, v175
	v_mul_f32_e32 v176, v68, v176
	v_mul_f32_e32 v177, v68, v177
	v_fmac_f32_e32 v174, v238, v32
	v_fmac_f32_e32 v175, v238, v33
	v_fmac_f32_e32 v176, v238, v34
	v_fmac_f32_e32 v177, v238, v35
	v_mul_f32_e32 v174, v178, v174
	v_mul_f32_e32 v175, v179, v175
	v_mul_f32_e32 v176, v180, v176
	v_mul_f32_e32 v177, v181, v177
	v_lshlrev_b32_e32 v168, 16, v116
	v_and_b32_e32 v169, 0xffff0000, v116
	v_lshlrev_b32_e32 v170, 16, v117
	v_and_b32_e32 v171, 0xffff0000, v117
	v_mul_f32_e32 v178, 0xbfb8aa3b, v168
	v_mul_f32_e32 v179, 0xbfb8aa3b, v169
	v_mul_f32_e32 v180, 0xbfb8aa3b, v170
	v_mul_f32_e32 v181, 0xbfb8aa3b, v171
	v_exp_f32_e32 v178, v178
	v_exp_f32_e32 v179, v179
	v_exp_f32_e32 v180, v180
	v_exp_f32_e32 v181, v181
	v_add_f32_e32 v178, 1.0, v178
	v_add_f32_e32 v179, 1.0, v179
	v_add_f32_e32 v180, 1.0, v180
	v_add_f32_e32 v181, 1.0, v181
	v_rcp_f32_e32 v178, v178
	v_rcp_f32_e32 v179, v179
	v_rcp_f32_e32 v180, v180
	v_rcp_f32_e32 v181, v181
	v_mul_f32_e32 v178, v178, v168
	v_mul_f32_e32 v179, v179, v169
	v_mul_f32_e32 v180, v180, v170
	v_mul_f32_e32 v181, v181, v171
	v_mul_f32_e32 v174, v174, v178
	v_mul_f32_e32 v175, v175, v179
	v_mul_f32_e32 v176, v176, v180
	v_mul_f32_e32 v177, v177, v181
	v_cvt_pk_bf16_f32 v182, v174, v175
	v_cvt_pk_bf16_f32 v183, v176, v177
	global_store_dwordx2 v234, v[182:183], s[6:7] offset:64
	v_and_b32_e32 v168, 0xffff0000, v118
	v_lshlrev_b32_e32 v169, 16, v119
	v_and_b32_e32 v170, 0xffff0000, v119
	v_lshlrev_b32_e32 v171, 16, v120
	v_and_b32_e32 v172, 0xffff0000, v120
	v_lshlrev_b32_e32 v173, 16, v121
	v_mul_f32_e32 v178, v83, v168
	v_fmac_f32_e32 v178, v82, v169
	v_fmac_f32_e32 v178, v80, v170
	v_add_f32_e32 v178, v70, v178
	v_mul_f32_e32 v179, v83, v169
	v_fmac_f32_e32 v179, v82, v170
	v_fmac_f32_e32 v179, v80, v171
	v_add_f32_e32 v179, v70, v179
	v_mul_f32_e32 v180, v83, v170
	v_fmac_f32_e32 v180, v82, v171
	v_fmac_f32_e32 v180, v80, v172
	v_add_f32_e32 v180, v70, v180
	v_mul_f32_e32 v181, v83, v171
	v_fmac_f32_e32 v181, v82, v172
	v_fmac_f32_e32 v181, v80, v173
	v_add_f32_e32 v181, v70, v181
	v_lshlrev_b32_e32 v174, 16, v162
	v_and_b32_e32 v175, 0xffff0000, v162
	v_lshlrev_b32_e32 v176, 16, v163
	v_and_b32_e32 v177, 0xffff0000, v163
	v_mul_f32_e32 v174, v68, v174
	v_mul_f32_e32 v175, v68, v175
	v_mul_f32_e32 v176, v68, v176
	v_mul_f32_e32 v177, v68, v177
	v_fmac_f32_e32 v174, v238, v36
	v_fmac_f32_e32 v175, v238, v37
	v_fmac_f32_e32 v176, v238, v38
	v_fmac_f32_e32 v177, v238, v39
	v_mul_f32_e32 v174, v178, v174
	v_mul_f32_e32 v175, v179, v175
	v_mul_f32_e32 v176, v180, v176
	v_mul_f32_e32 v177, v181, v177
	v_lshlrev_b32_e32 v168, 16, v122
	v_and_b32_e32 v169, 0xffff0000, v122
	v_lshlrev_b32_e32 v170, 16, v123
	v_and_b32_e32 v171, 0xffff0000, v123
	v_mul_f32_e32 v178, 0xbfb8aa3b, v168
	v_mul_f32_e32 v179, 0xbfb8aa3b, v169
	v_mul_f32_e32 v180, 0xbfb8aa3b, v170
	v_mul_f32_e32 v181, 0xbfb8aa3b, v171
	v_exp_f32_e32 v178, v178
	v_exp_f32_e32 v179, v179
	v_exp_f32_e32 v180, v180
	v_exp_f32_e32 v181, v181
	v_add_f32_e32 v178, 1.0, v178
	v_add_f32_e32 v179, 1.0, v179
	v_add_f32_e32 v180, 1.0, v180
	v_add_f32_e32 v181, 1.0, v181
	v_rcp_f32_e32 v178, v178
	v_rcp_f32_e32 v179, v179
	v_rcp_f32_e32 v180, v180
	v_rcp_f32_e32 v181, v181
	v_mul_f32_e32 v178, v178, v168
	v_mul_f32_e32 v179, v179, v169
	v_mul_f32_e32 v180, v180, v170
	v_mul_f32_e32 v181, v181, v171
	v_mul_f32_e32 v174, v174, v178
	v_mul_f32_e32 v175, v175, v179
	v_mul_f32_e32 v176, v176, v180
	v_mul_f32_e32 v177, v177, v181
	v_cvt_pk_bf16_f32 v182, v174, v175
	v_cvt_pk_bf16_f32 v183, v176, v177
	global_store_dwordx2 v234, v[182:183], s[6:7] offset:80
	v_and_b32_e32 v168, 0xffff0000, v124
	v_lshlrev_b32_e32 v169, 16, v125
	v_and_b32_e32 v170, 0xffff0000, v125
	v_lshlrev_b32_e32 v171, 16, v126
	v_and_b32_e32 v172, 0xffff0000, v126
	v_lshlrev_b32_e32 v173, 16, v127
	v_mul_f32_e32 v178, v83, v168
	v_fmac_f32_e32 v178, v82, v169
	v_fmac_f32_e32 v178, v80, v170
	v_add_f32_e32 v178, v70, v178
	v_mul_f32_e32 v179, v83, v169
	v_fmac_f32_e32 v179, v82, v170
	v_fmac_f32_e32 v179, v80, v171
	v_add_f32_e32 v179, v70, v179
	v_mul_f32_e32 v180, v83, v170
	v_fmac_f32_e32 v180, v82, v171
	v_fmac_f32_e32 v180, v80, v172
	v_add_f32_e32 v180, v70, v180
	v_mul_f32_e32 v181, v83, v171
	v_fmac_f32_e32 v181, v82, v172
	v_fmac_f32_e32 v181, v80, v173
	v_add_f32_e32 v181, v70, v181
	v_lshlrev_b32_e32 v174, 16, v164
	v_and_b32_e32 v175, 0xffff0000, v164
	v_lshlrev_b32_e32 v176, 16, v165
	v_and_b32_e32 v177, 0xffff0000, v165
	v_mul_f32_e32 v174, v68, v174
	v_mul_f32_e32 v175, v68, v175
	v_mul_f32_e32 v176, v68, v176
	v_mul_f32_e32 v177, v68, v177
	v_fmac_f32_e32 v174, v238, v40
	v_fmac_f32_e32 v175, v238, v41
	v_fmac_f32_e32 v176, v238, v42
	v_fmac_f32_e32 v177, v238, v43
	v_mul_f32_e32 v174, v178, v174
	v_mul_f32_e32 v175, v179, v175
	v_mul_f32_e32 v176, v180, v176
	v_mul_f32_e32 v177, v181, v177
	v_lshlrev_b32_e32 v168, 16, v128
	v_and_b32_e32 v169, 0xffff0000, v128
	v_lshlrev_b32_e32 v170, 16, v129
	v_and_b32_e32 v171, 0xffff0000, v129
	v_mul_f32_e32 v178, 0xbfb8aa3b, v168
	v_mul_f32_e32 v179, 0xbfb8aa3b, v169
	v_mul_f32_e32 v180, 0xbfb8aa3b, v170
	v_mul_f32_e32 v181, 0xbfb8aa3b, v171
	v_exp_f32_e32 v178, v178
	v_exp_f32_e32 v179, v179
	v_exp_f32_e32 v180, v180
	v_exp_f32_e32 v181, v181
	v_add_f32_e32 v178, 1.0, v178
	v_add_f32_e32 v179, 1.0, v179
	v_add_f32_e32 v180, 1.0, v180
	v_add_f32_e32 v181, 1.0, v181
	v_rcp_f32_e32 v178, v178
	v_rcp_f32_e32 v179, v179
	v_rcp_f32_e32 v180, v180
; DI float bflo(unsigned v) { return __uint_as_float(v << 16); }
; DI float bfhi(unsigned v) { return __uint_as_float(v & 0xffff0000u); }
; DI float siluf(float x) { return x * __builtin_amdgcn_rcpf(1.f + __expf(-x)); }
; DI void hyena_item(const P& p, int l, int c, char* smem) {
;     ...
; #pragma unroll
;     for (int I = 0; I < 4; ++I)
; #pragma unroll
;       for (int rq = 0; rq < 4; ++rq) {
;         const int bq = 32 * I + 8 * rq + 4 * g;
;         const int t4 = 128 * a + bq;
;         float px[4];
;         sconv4(rowx, t4, x0, x1, x2, xb, px);
;         const uint2 zv = *(const uint2*)(U + (bt * 64 + a) * 136 + bq);
;         const uint2 gv = *(const uint2*)(rowg + t4);
;         const float z1[4] = {bflo(zv.x), bfhi(zv.x), bflo(zv.y), bfhi(zv.y)};
;         const float gt[4] = {bflo(gv.x), bfhi(gv.x), bflo(gv.y), bfhi(gv.y)};
;         float yy[4];
; #pragma unroll
;         for (int j = 0; j < 4; ++j) yy[j] = px[j] * (acc[I][4 * rq + j] * invn1 + z1[j] * d1) * siluf(gt[j]);
;         uint2 ov; ov.x = pack2(yy[0], yy[1]); ov.y = pack2(yy[2], yy[3]);
;         *(uint2*)(dst + t4) = ov;
;       }
	v_rcp_f32_e32 v181, v181
	v_mul_f32_e32 v178, v178, v168
	v_mul_f32_e32 v179, v179, v169
	v_mul_f32_e32 v180, v180, v170
	v_mul_f32_e32 v181, v181, v171
	v_mul_f32_e32 v174, v174, v178
	v_mul_f32_e32 v175, v175, v179
	v_mul_f32_e32 v176, v176, v180
	v_mul_f32_e32 v177, v177, v181
	v_cvt_pk_bf16_f32 v182, v174, v175
	v_cvt_pk_bf16_f32 v183, v176, v177
	global_store_dwordx2 v234, v[182:183], s[6:7] offset:96
	v_and_b32_e32 v168, 0xffff0000, v130
	v_lshlrev_b32_e32 v169, 16, v131
	v_and_b32_e32 v170, 0xffff0000, v131
	v_lshlrev_b32_e32 v171, 16, v132
	v_and_b32_e32 v172, 0xffff0000, v132
	v_lshlrev_b32_e32 v173, 16, v133
	v_mul_f32_e32 v178, v83, v168
	v_fmac_f32_e32 v178, v82, v169
	v_fmac_f32_e32 v178, v80, v170
	v_add_f32_e32 v178, v70, v178
	v_mul_f32_e32 v179, v83, v169
	v_fmac_f32_e32 v179, v82, v170
	v_fmac_f32_e32 v179, v80, v171
	v_add_f32_e32 v179, v70, v179
	v_mul_f32_e32 v180, v83, v170
	v_fmac_f32_e32 v180, v82, v171
	v_fmac_f32_e32 v180, v80, v172
	v_add_f32_e32 v180, v70, v180
	v_mul_f32_e32 v181, v83, v171
	v_fmac_f32_e32 v181, v82, v172
	v_fmac_f32_e32 v181, v80, v173
	v_add_f32_e32 v181, v70, v181
	v_lshlrev_b32_e32 v174, 16, v166
	v_and_b32_e32 v175, 0xffff0000, v166
	v_lshlrev_b32_e32 v176, 16, v167
	v_and_b32_e32 v177, 0xffff0000, v167
	v_mul_f32_e32 v174, v68, v174
	v_mul_f32_e32 v175, v68, v175
	v_mul_f32_e32 v176, v68, v176
	v_mul_f32_e32 v177, v68, v177
	v_fmac_f32_e32 v174, v238, v44
	v_fmac_f32_e32 v175, v238, v45
	v_fmac_f32_e32 v176, v238, v46
	v_fmac_f32_e32 v177, v238, v47
	v_mul_f32_e32 v174, v178, v174
	v_mul_f32_e32 v175, v179, v175
	v_mul_f32_e32 v176, v180, v176
	v_mul_f32_e32 v177, v181, v177
	v_lshlrev_b32_e32 v168, 16, v134
	v_and_b32_e32 v169, 0xffff0000, v134
	v_lshlrev_b32_e32 v170, 16, v135
	v_and_b32_e32 v171, 0xffff0000, v135
	v_mul_f32_e32 v178, 0xbfb8aa3b, v168
	v_mul_f32_e32 v179, 0xbfb8aa3b, v169
	v_mul_f32_e32 v180, 0xbfb8aa3b, v170
	v_mul_f32_e32 v181, 0xbfb8aa3b, v171
	v_exp_f32_e32 v178, v178
	v_exp_f32_e32 v179, v179
	v_exp_f32_e32 v180, v180
	v_exp_f32_e32 v181, v181
	v_add_f32_e32 v178, 1.0, v178
	v_add_f32_e32 v179, 1.0, v179
	v_add_f32_e32 v180, 1.0, v180
	v_add_f32_e32 v181, 1.0, v181
	v_rcp_f32_e32 v178, v178
	v_rcp_f32_e32 v179, v179
	v_rcp_f32_e32 v180, v180
	v_rcp_f32_e32 v181, v181
	v_mul_f32_e32 v178, v178, v168
	v_mul_f32_e32 v179, v179, v169
	v_mul_f32_e32 v180, v180, v170
	v_mul_f32_e32 v181, v181, v171
	v_mul_f32_e32 v174, v174, v178
	v_mul_f32_e32 v175, v175, v179
	v_mul_f32_e32 v176, v176, v180
	v_mul_f32_e32 v177, v177, v181
	v_cvt_pk_bf16_f32 v182, v174, v175
	v_cvt_pk_bf16_f32 v183, v176, v177
	global_store_dwordx2 v234, v[182:183], s[6:7] offset:112
	global_load_dwordx4 v[88:91], v234, s[98:99] offset:192
	global_load_dwordx2 v[92:93], v234, s[100:101] offset:192
	global_load_dwordx4 v[94:97], v234, s[98:99] offset:208
	global_load_dwordx2 v[98:99], v234, s[100:101] offset:208
	global_load_dwordx4 v[100:103], v234, s[98:99] offset:224
	global_load_dwordx2 v[104:105], v234, s[100:101] offset:224
	global_load_dwordx4 v[106:109], v234, s[98:99] offset:240
	global_load_dwordx2 v[110:111], v234, s[100:101] offset:240
	s_waitcnt vmcnt(12)
	ds_read_b64 v[160:161], v235 offset:128
	ds_read_b64 v[162:163], v235 offset:144
	ds_read_b64 v[164:165], v235 offset:160
	ds_read_b64 v[166:167], v235 offset:176
	v_and_b32_e32 v168, 0xffff0000, v136
	v_lshlrev_b32_e32 v169, 16, v137
	v_and_b32_e32 v170, 0xffff0000, v137
	v_lshlrev_b32_e32 v171, 16, v138
	v_and_b32_e32 v172, 0xffff0000, v138
	v_lshlrev_b32_e32 v173, 16, v139
	v_mul_f32_e32 v178, v83, v168
	v_fmac_f32_e32 v178, v82, v169
	v_fmac_f32_e32 v178, v80, v170
	v_add_f32_e32 v178, v70, v178
	v_mul_f32_e32 v179, v83, v169
	v_fmac_f32_e32 v179, v82, v170
	v_fmac_f32_e32 v179, v80, v171
	v_add_f32_e32 v179, v70, v179
	v_mul_f32_e32 v180, v83, v170
	v_fmac_f32_e32 v180, v82, v171
	v_fmac_f32_e32 v180, v80, v172
	v_add_f32_e32 v180, v70, v180
	v_mul_f32_e32 v181, v83, v171
	v_fmac_f32_e32 v181, v82, v172
	v_fmac_f32_e32 v181, v80, v173
	v_add_f32_e32 v181, v70, v181
	s_waitcnt lgkmcnt(0)
	v_lshlrev_b32_e32 v174, 16, v160
	v_and_b32_e32 v175, 0xffff0000, v160
	v_lshlrev_b32_e32 v176, 16, v161
	v_and_b32_e32 v177, 0xffff0000, v161
	v_mul_f32_e32 v174, v68, v174
	v_mul_f32_e32 v175, v68, v175
	v_mul_f32_e32 v176, v68, v176
	v_mul_f32_e32 v177, v68, v177
	v_fmac_f32_e32 v174, v238, v16
	v_fmac_f32_e32 v175, v238, v17
	v_fmac_f32_e32 v176, v238, v18
	v_fmac_f32_e32 v177, v238, v19
	v_mul_f32_e32 v174, v178, v174
	v_mul_f32_e32 v175, v179, v175
	v_mul_f32_e32 v176, v180, v176
	v_mul_f32_e32 v177, v181, v177
	v_lshlrev_b32_e32 v168, 16, v140
	v_and_b32_e32 v169, 0xffff0000, v140
	v_lshlrev_b32_e32 v170, 16, v141
	v_and_b32_e32 v171, 0xffff0000, v141
	v_mul_f32_e32 v178, 0xbfb8aa3b, v168
	v_mul_f32_e32 v179, 0xbfb8aa3b, v169
	v_mul_f32_e32 v180, 0xbfb8aa3b, v170
	v_mul_f32_e32 v181, 0xbfb8aa3b, v171
	v_exp_f32_e32 v178, v178
	v_exp_f32_e32 v179, v179
	v_exp_f32_e32 v180, v180
	v_exp_f32_e32 v181, v181
	v_add_f32_e32 v178, 1.0, v178
	v_add_f32_e32 v179, 1.0, v179
	v_add_f32_e32 v180, 1.0, v180
	v_add_f32_e32 v181, 1.0, v181
	v_rcp_f32_e32 v178, v178
	v_rcp_f32_e32 v179, v179
	v_rcp_f32_e32 v180, v180
	v_rcp_f32_e32 v181, v181
	v_mul_f32_e32 v178, v178, v168
	v_mul_f32_e32 v179, v179, v169
	v_mul_f32_e32 v180, v180, v170
	v_mul_f32_e32 v181, v181, v171
	v_mul_f32_e32 v174, v174, v178
	v_mul_f32_e32 v175, v175, v179
	v_mul_f32_e32 v176, v176, v180
	v_mul_f32_e32 v177, v177, v181
	v_cvt_pk_bf16_f32 v182, v174, v175
	v_cvt_pk_bf16_f32 v183, v176, v177
	global_store_dwordx2 v234, v[182:183], s[6:7] offset:128
	v_and_b32_e32 v168, 0xffff0000, v142
; DI float bflo(unsigned v) { return __uint_as_float(v << 16); }
; DI float bfhi(unsigned v) { return __uint_as_float(v & 0xffff0000u); }
; DI float siluf(float x) { return x * __builtin_amdgcn_rcpf(1.f + __expf(-x)); }
; DI void hyena_item(const P& p, int l, int c, char* smem) {
;     ...
;     for (int I = 0; I < 4; ++I)
; #pragma unroll
;       for (int rq = 0; rq < 4; ++rq) {
;         const int bq = 32 * I + 8 * rq + 4 * g;
;         const int t4 = 128 * a + bq;
;         float px[4];
;         sconv4(rowx, t4, x0, x1, x2, xb, px);
;         const uint2 zv = *(const uint2*)(U + (bt * 64 + a) * 136 + bq);
;         const uint2 gv = *(const uint2*)(rowg + t4);
;         const float z1[4] = {bflo(zv.x), bfhi(zv.x), bflo(zv.y), bfhi(zv.y)};
;         const float gt[4] = {bflo(gv.x), bfhi(gv.x), bflo(gv.y), bfhi(gv.y)};
;         float yy[4];
; #pragma unroll
;         for (int j = 0; j < 4; ++j) yy[j] = px[j] * (acc[I][4 * rq + j] * invn1 + z1[j] * d1) * siluf(gt[j]);
;         uint2 ov; ov.x = pack2(yy[0], yy[1]); ov.y = pack2(yy[2], yy[3]);
;         *(uint2*)(dst + t4) = ov;
;       }
	v_lshlrev_b32_e32 v169, 16, v143
	v_and_b32_e32 v170, 0xffff0000, v143
	v_lshlrev_b32_e32 v171, 16, v144
	v_and_b32_e32 v172, 0xffff0000, v144
	v_lshlrev_b32_e32 v173, 16, v145
	v_mul_f32_e32 v178, v83, v168
	v_fmac_f32_e32 v178, v82, v169
	v_fmac_f32_e32 v178, v80, v170
	v_add_f32_e32 v178, v70, v178
	v_mul_f32_e32 v179, v83, v169
	v_fmac_f32_e32 v179, v82, v170
	v_fmac_f32_e32 v179, v80, v171
	v_add_f32_e32 v179, v70, v179
	v_mul_f32_e32 v180, v83, v170
	v_fmac_f32_e32 v180, v82, v171
	v_fmac_f32_e32 v180, v80, v172
	v_add_f32_e32 v180, v70, v180
	v_mul_f32_e32 v181, v83, v171
	v_fmac_f32_e32 v181, v82, v172
	v_fmac_f32_e32 v181, v80, v173
	v_add_f32_e32 v181, v70, v181
	v_lshlrev_b32_e32 v174, 16, v162
	v_and_b32_e32 v175, 0xffff0000, v162
	v_lshlrev_b32_e32 v176, 16, v163
	v_and_b32_e32 v177, 0xffff0000, v163
	v_mul_f32_e32 v174, v68, v174
	v_mul_f32_e32 v175, v68, v175
	v_mul_f32_e32 v176, v68, v176
	v_mul_f32_e32 v177, v68, v177
	v_fmac_f32_e32 v174, v238, v20
	v_fmac_f32_e32 v175, v238, v21
	v_fmac_f32_e32 v176, v238, v22
	v_fmac_f32_e32 v177, v238, v23
	v_mul_f32_e32 v174, v178, v174
	v_mul_f32_e32 v175, v179, v175
	v_mul_f32_e32 v176, v180, v176
	v_mul_f32_e32 v177, v181, v177
	v_lshlrev_b32_e32 v168, 16, v146
	v_and_b32_e32 v169, 0xffff0000, v146
	v_lshlrev_b32_e32 v170, 16, v147
	v_and_b32_e32 v171, 0xffff0000, v147
	v_mul_f32_e32 v178, 0xbfb8aa3b, v168
	v_mul_f32_e32 v179, 0xbfb8aa3b, v169
	v_mul_f32_e32 v180, 0xbfb8aa3b, v170
	v_mul_f32_e32 v181, 0xbfb8aa3b, v171
	v_exp_f32_e32 v178, v178
	v_exp_f32_e32 v179, v179
	v_exp_f32_e32 v180, v180
	v_exp_f32_e32 v181, v181
	v_add_f32_e32 v178, 1.0, v178
	v_add_f32_e32 v179, 1.0, v179
	v_add_f32_e32 v180, 1.0, v180
	v_add_f32_e32 v181, 1.0, v181
	v_rcp_f32_e32 v178, v178
	v_rcp_f32_e32 v179, v179
	v_rcp_f32_e32 v180, v180
	v_rcp_f32_e32 v181, v181
	v_mul_f32_e32 v178, v178, v168
	v_mul_f32_e32 v179, v179, v169
	v_mul_f32_e32 v180, v180, v170
	v_mul_f32_e32 v181, v181, v171
	v_mul_f32_e32 v174, v174, v178
	v_mul_f32_e32 v175, v175, v179
	v_mul_f32_e32 v176, v176, v180
	v_mul_f32_e32 v177, v177, v181
	v_cvt_pk_bf16_f32 v182, v174, v175
	v_cvt_pk_bf16_f32 v183, v176, v177
	global_store_dwordx2 v234, v[182:183], s[6:7] offset:144
	v_and_b32_e32 v168, 0xffff0000, v148
	v_lshlrev_b32_e32 v169, 16, v149
	v_and_b32_e32 v170, 0xffff0000, v149
	v_lshlrev_b32_e32 v171, 16, v150
	v_and_b32_e32 v172, 0xffff0000, v150
	v_lshlrev_b32_e32 v173, 16, v151
	v_mul_f32_e32 v178, v83, v168
	v_fmac_f32_e32 v178, v82, v169
	v_fmac_f32_e32 v178, v80, v170
	v_add_f32_e32 v178, v70, v178
	v_mul_f32_e32 v179, v83, v169
	v_fmac_f32_e32 v179, v82, v170
	v_fmac_f32_e32 v179, v80, v171
	v_add_f32_e32 v179, v70, v179
	v_mul_f32_e32 v180, v83, v170
	v_fmac_f32_e32 v180, v82, v171
	v_fmac_f32_e32 v180, v80, v172
	v_add_f32_e32 v180, v70, v180
	v_mul_f32_e32 v181, v83, v171
	v_fmac_f32_e32 v181, v82, v172
	v_fmac_f32_e32 v181, v80, v173
	v_add_f32_e32 v181, v70, v181
	v_lshlrev_b32_e32 v174, 16, v164
	v_and_b32_e32 v175, 0xffff0000, v164
	v_lshlrev_b32_e32 v176, 16, v165
	v_and_b32_e32 v177, 0xffff0000, v165
	v_mul_f32_e32 v174, v68, v174
	v_mul_f32_e32 v175, v68, v175
	v_mul_f32_e32 v176, v68, v176
	v_mul_f32_e32 v177, v68, v177
	v_fmac_f32_e32 v174, v238, v24
	v_fmac_f32_e32 v175, v238, v25
	v_fmac_f32_e32 v176, v238, v26
	v_fmac_f32_e32 v177, v238, v27
	v_mul_f32_e32 v174, v178, v174
	v_mul_f32_e32 v175, v179, v175
	v_mul_f32_e32 v176, v180, v176
	v_mul_f32_e32 v177, v181, v177
	v_lshlrev_b32_e32 v168, 16, v152
	v_and_b32_e32 v169, 0xffff0000, v152
	v_lshlrev_b32_e32 v170, 16, v153
	v_and_b32_e32 v171, 0xffff0000, v153
	v_mul_f32_e32 v178, 0xbfb8aa3b, v168
	v_mul_f32_e32 v179, 0xbfb8aa3b, v169
	v_mul_f32_e32 v180, 0xbfb8aa3b, v170
	v_mul_f32_e32 v181, 0xbfb8aa3b, v171
	v_exp_f32_e32 v178, v178
	v_exp_f32_e32 v179, v179
	v_exp_f32_e32 v180, v180
	v_exp_f32_e32 v181, v181
	v_add_f32_e32 v178, 1.0, v178
	v_add_f32_e32 v179, 1.0, v179
	v_add_f32_e32 v180, 1.0, v180
	v_add_f32_e32 v181, 1.0, v181
	v_rcp_f32_e32 v178, v178
	v_rcp_f32_e32 v179, v179
	v_rcp_f32_e32 v180, v180
	v_rcp_f32_e32 v181, v181
	v_mul_f32_e32 v178, v178, v168
	v_mul_f32_e32 v179, v179, v169
	v_mul_f32_e32 v180, v180, v170
	v_mul_f32_e32 v181, v181, v171
	v_mul_f32_e32 v174, v174, v178
	v_mul_f32_e32 v175, v175, v179
	v_mul_f32_e32 v176, v176, v180
	v_mul_f32_e32 v177, v177, v181
	v_cvt_pk_bf16_f32 v182, v174, v175
	v_cvt_pk_bf16_f32 v183, v176, v177
	global_store_dwordx2 v234, v[182:183], s[6:7] offset:160
	v_and_b32_e32 v168, 0xffff0000, v154
	v_lshlrev_b32_e32 v169, 16, v155
	v_and_b32_e32 v170, 0xffff0000, v155
	v_lshlrev_b32_e32 v171, 16, v156
	v_and_b32_e32 v172, 0xffff0000, v156
	v_lshlrev_b32_e32 v173, 16, v157
	v_mul_f32_e32 v178, v83, v168
	v_fmac_f32_e32 v178, v82, v169
	v_fmac_f32_e32 v178, v80, v170
	v_add_f32_e32 v178, v70, v178
	v_mul_f32_e32 v179, v83, v169
	v_fmac_f32_e32 v179, v82, v170
	v_fmac_f32_e32 v179, v80, v171
	v_add_f32_e32 v179, v70, v179
	v_mul_f32_e32 v180, v83, v170
	v_fmac_f32_e32 v180, v82, v171
	v_fmac_f32_e32 v180, v80, v172
	v_add_f32_e32 v180, v70, v180
	v_mul_f32_e32 v181, v83, v171
	v_fmac_f32_e32 v181, v82, v172
	v_fmac_f32_e32 v181, v80, v173
	v_add_f32_e32 v181, v70, v181
	v_lshlrev_b32_e32 v174, 16, v166
	v_and_b32_e32 v175, 0xffff0000, v166
	v_lshlrev_b32_e32 v176, 16, v167
	v_and_b32_e32 v177, 0xffff0000, v167
	v_mul_f32_e32 v174, v68, v174
	v_mul_f32_e32 v175, v68, v175
	v_mul_f32_e32 v176, v68, v176
	v_mul_f32_e32 v177, v68, v177
	v_fmac_f32_e32 v174, v238, v28
	v_fmac_f32_e32 v175, v238, v29
	v_fmac_f32_e32 v176, v238, v30
	v_fmac_f32_e32 v177, v238, v31
	v_mul_f32_e32 v174, v178, v174
	v_mul_f32_e32 v175, v179, v175
	v_mul_f32_e32 v176, v180, v176
	v_mul_f32_e32 v177, v181, v177
	v_lshlrev_b32_e32 v168, 16, v158
	v_and_b32_e32 v169, 0xffff0000, v158
	v_lshlrev_b32_e32 v170, 16, v159
	v_and_b32_e32 v171, 0xffff0000, v159
	v_mul_f32_e32 v178, 0xbfb8aa3b, v168
	v_mul_f32_e32 v179, 0xbfb8aa3b, v169
	v_mul_f32_e32 v180, 0xbfb8aa3b, v170
	v_mul_f32_e32 v181, 0xbfb8aa3b, v171
	v_exp_f32_e32 v178, v178
	v_exp_f32_e32 v179, v179
	v_exp_f32_e32 v180, v180
	v_exp_f32_e32 v181, v181
	v_add_f32_e32 v178, 1.0, v178
	v_add_f32_e32 v179, 1.0, v179
	v_add_f32_e32 v180, 1.0, v180
	v_add_f32_e32 v181, 1.0, v181
	v_rcp_f32_e32 v178, v178
	v_rcp_f32_e32 v179, v179
	v_rcp_f32_e32 v180, v180
	v_rcp_f32_e32 v181, v181
	v_mul_f32_e32 v178, v178, v168
	v_mul_f32_e32 v179, v179, v169
	v_mul_f32_e32 v180, v180, v170
	v_mul_f32_e32 v181, v181, v171
	v_mul_f32_e32 v174, v174, v178
	v_mul_f32_e32 v175, v175, v179
	v_mul_f32_e32 v176, v176, v180
	v_mul_f32_e32 v177, v177, v181
	v_cvt_pk_bf16_f32 v182, v174, v175
	v_cvt_pk_bf16_f32 v183, v176, v177
	global_store_dwordx2 v234, v[182:183], s[6:7] offset:176
	s_waitcnt vmcnt(4)
; DI float bflo(unsigned v) { return __uint_as_float(v << 16); }
; DI float bfhi(unsigned v) { return __uint_as_float(v & 0xffff0000u); }
; DI float siluf(float x) { return x * __builtin_amdgcn_rcpf(1.f + __expf(-x)); }
; DI void hyena_item(const P& p, int l, int c, char* smem) {
;     ...
;     for (int I = 0; I < 4; ++I)
; #pragma unroll
;       for (int rq = 0; rq < 4; ++rq) {
;         const int bq = 32 * I + 8 * rq + 4 * g;
;         const int t4 = 128 * a + bq;
;         float px[4];
;         sconv4(rowx, t4, x0, x1, x2, xb, px);
;         const uint2 zv = *(const uint2*)(U + (bt * 64 + a) * 136 + bq);
;         const uint2 gv = *(const uint2*)(rowg + t4);
;         const float z1[4] = {bflo(zv.x), bfhi(zv.x), bflo(zv.y), bfhi(zv.y)};
;         const float gt[4] = {bflo(gv.x), bfhi(gv.x), bflo(gv.y), bfhi(gv.y)};
;         float yy[4];
; #pragma unroll
;         for (int j = 0; j < 4; ++j) yy[j] = px[j] * (acc[I][4 * rq + j] * invn1 + z1[j] * d1) * siluf(gt[j]);
;         uint2 ov; ov.x = pack2(yy[0], yy[1]); ov.y = pack2(yy[2], yy[3]);
;         *(uint2*)(dst + t4) = ov;
;       }
	ds_read_b64 v[160:161], v235 offset:192
	ds_read_b64 v[162:163], v235 offset:208
	ds_read_b64 v[164:165], v235 offset:224
	ds_read_b64 v[166:167], v235 offset:240
	v_and_b32_e32 v168, 0xffff0000, v88
	v_lshlrev_b32_e32 v169, 16, v89
	v_and_b32_e32 v170, 0xffff0000, v89
	v_lshlrev_b32_e32 v171, 16, v90
	v_and_b32_e32 v172, 0xffff0000, v90
	v_lshlrev_b32_e32 v173, 16, v91
	v_mul_f32_e32 v178, v83, v168
	v_fmac_f32_e32 v178, v82, v169
	v_fmac_f32_e32 v178, v80, v170
	v_add_f32_e32 v178, v70, v178
	v_mul_f32_e32 v179, v83, v169
	v_fmac_f32_e32 v179, v82, v170
	v_fmac_f32_e32 v179, v80, v171
	v_add_f32_e32 v179, v70, v179
	v_mul_f32_e32 v180, v83, v170
	v_fmac_f32_e32 v180, v82, v171
	v_fmac_f32_e32 v180, v80, v172
	v_add_f32_e32 v180, v70, v180
	v_mul_f32_e32 v181, v83, v171
	v_fmac_f32_e32 v181, v82, v172
	v_fmac_f32_e32 v181, v80, v173
	v_add_f32_e32 v181, v70, v181
	s_waitcnt lgkmcnt(0)
	v_lshlrev_b32_e32 v174, 16, v160
	v_and_b32_e32 v175, 0xffff0000, v160
	v_lshlrev_b32_e32 v176, 16, v161
	v_and_b32_e32 v177, 0xffff0000, v161
	v_mul_f32_e32 v174, v68, v174
	v_mul_f32_e32 v175, v68, v175
	v_mul_f32_e32 v176, v68, v176
	v_mul_f32_e32 v177, v68, v177
	v_fmac_f32_e32 v174, v238, v0
	v_fmac_f32_e32 v175, v238, v1
	v_fmac_f32_e32 v176, v238, v2
	v_fmac_f32_e32 v177, v238, v3
	v_mul_f32_e32 v174, v178, v174
	v_mul_f32_e32 v175, v179, v175
	v_mul_f32_e32 v176, v180, v176
	v_mul_f32_e32 v177, v181, v177
	v_lshlrev_b32_e32 v168, 16, v92
	v_and_b32_e32 v169, 0xffff0000, v92
	v_lshlrev_b32_e32 v170, 16, v93
	v_and_b32_e32 v171, 0xffff0000, v93
	v_mul_f32_e32 v178, 0xbfb8aa3b, v168
	v_mul_f32_e32 v179, 0xbfb8aa3b, v169
	v_mul_f32_e32 v180, 0xbfb8aa3b, v170
	v_mul_f32_e32 v181, 0xbfb8aa3b, v171
	v_exp_f32_e32 v178, v178
	v_exp_f32_e32 v179, v179
	v_exp_f32_e32 v180, v180
	v_exp_f32_e32 v181, v181
	v_add_f32_e32 v178, 1.0, v178
	v_add_f32_e32 v179, 1.0, v179
	v_add_f32_e32 v180, 1.0, v180
	v_add_f32_e32 v181, 1.0, v181
	v_rcp_f32_e32 v178, v178
	v_rcp_f32_e32 v179, v179
	v_rcp_f32_e32 v180, v180
	v_rcp_f32_e32 v181, v181
	v_mul_f32_e32 v178, v178, v168
	v_mul_f32_e32 v179, v179, v169
	v_mul_f32_e32 v180, v180, v170
	v_mul_f32_e32 v181, v181, v171
	v_mul_f32_e32 v174, v174, v178
	v_mul_f32_e32 v175, v175, v179
	v_mul_f32_e32 v176, v176, v180
	v_mul_f32_e32 v177, v177, v181
	v_cvt_pk_bf16_f32 v182, v174, v175
	v_cvt_pk_bf16_f32 v183, v176, v177
	global_store_dwordx2 v234, v[182:183], s[6:7] offset:192
	v_and_b32_e32 v168, 0xffff0000, v94
	v_lshlrev_b32_e32 v169, 16, v95
	v_and_b32_e32 v170, 0xffff0000, v95
	v_lshlrev_b32_e32 v171, 16, v96
	v_and_b32_e32 v172, 0xffff0000, v96
	v_lshlrev_b32_e32 v173, 16, v97
	v_mul_f32_e32 v178, v83, v168
	v_fmac_f32_e32 v178, v82, v169
	v_fmac_f32_e32 v178, v80, v170
	v_add_f32_e32 v178, v70, v178
	v_mul_f32_e32 v179, v83, v169
	v_fmac_f32_e32 v179, v82, v170
	v_fmac_f32_e32 v179, v80, v171
	v_add_f32_e32 v179, v70, v179
	v_mul_f32_e32 v180, v83, v170
	v_fmac_f32_e32 v180, v82, v171
	v_fmac_f32_e32 v180, v80, v172
	v_add_f32_e32 v180, v70, v180
	v_mul_f32_e32 v181, v83, v171
	v_fmac_f32_e32 v181, v82, v172
	v_fmac_f32_e32 v181, v80, v173
	v_add_f32_e32 v181, v70, v181
	v_lshlrev_b32_e32 v174, 16, v162
	v_and_b32_e32 v175, 0xffff0000, v162
	v_lshlrev_b32_e32 v176, 16, v163
	v_and_b32_e32 v177, 0xffff0000, v163
	v_mul_f32_e32 v174, v68, v174
	v_mul_f32_e32 v175, v68, v175
	v_mul_f32_e32 v176, v68, v176
	v_mul_f32_e32 v177, v68, v177
	v_fmac_f32_e32 v174, v238, v4
	v_fmac_f32_e32 v175, v238, v5
	v_fmac_f32_e32 v176, v238, v6
	v_fmac_f32_e32 v177, v238, v7
	v_mul_f32_e32 v174, v178, v174
	v_mul_f32_e32 v175, v179, v175
	v_mul_f32_e32 v176, v180, v176
	v_mul_f32_e32 v177, v181, v177
	v_lshlrev_b32_e32 v168, 16, v98
	v_and_b32_e32 v169, 0xffff0000, v98
	v_lshlrev_b32_e32 v170, 16, v99
	v_and_b32_e32 v171, 0xffff0000, v99
	v_mul_f32_e32 v178, 0xbfb8aa3b, v168
	v_mul_f32_e32 v179, 0xbfb8aa3b, v169
	v_mul_f32_e32 v180, 0xbfb8aa3b, v170
	v_mul_f32_e32 v181, 0xbfb8aa3b, v171
	v_exp_f32_e32 v178, v178
	v_exp_f32_e32 v179, v179
	v_exp_f32_e32 v180, v180
	v_exp_f32_e32 v181, v181
	v_add_f32_e32 v178, 1.0, v178
	v_add_f32_e32 v179, 1.0, v179
	v_add_f32_e32 v180, 1.0, v180
	v_add_f32_e32 v181, 1.0, v181
	v_rcp_f32_e32 v178, v178
	v_rcp_f32_e32 v179, v179
	v_rcp_f32_e32 v180, v180
	v_rcp_f32_e32 v181, v181
	v_mul_f32_e32 v178, v178, v168
	v_mul_f32_e32 v179, v179, v169
	v_mul_f32_e32 v180, v180, v170
	v_mul_f32_e32 v181, v181, v171
	v_mul_f32_e32 v174, v174, v178
	v_mul_f32_e32 v175, v175, v179
	v_mul_f32_e32 v176, v176, v180
	v_mul_f32_e32 v177, v177, v181
	v_cvt_pk_bf16_f32 v182, v174, v175
	v_cvt_pk_bf16_f32 v183, v176, v177
	global_store_dwordx2 v234, v[182:183], s[6:7] offset:208
; DI float bflo(unsigned v) { return __uint_as_float(v << 16); }
; DI float bfhi(unsigned v) { return __uint_as_float(v & 0xffff0000u); }
; DI float siluf(float x) { return x * __builtin_amdgcn_rcpf(1.f + __expf(-x)); }
; DI void hyena_item(const P& p, int l, int c, char* smem) {
;     ...
;     for (int I = 0; I < 4; ++I)
; #pragma unroll
;       for (int rq = 0; rq < 4; ++rq) {
;         const int bq = 32 * I + 8 * rq + 4 * g;
;         const int t4 = 128 * a + bq;
;         float px[4];
;         sconv4(rowx, t4, x0, x1, x2, xb, px);
;         const uint2 zv = *(const uint2*)(U + (bt * 64 + a) * 136 + bq);
;         const uint2 gv = *(const uint2*)(rowg + t4);
;         const float z1[4] = {bflo(zv.x), bfhi(zv.x), bflo(zv.y), bfhi(zv.y)};
;         const float gt[4] = {bflo(gv.x), bfhi(gv.x), bflo(gv.y), bfhi(gv.y)};
;         float yy[4];
; #pragma unroll
;         for (int j = 0; j < 4; ++j) yy[j] = px[j] * (acc[I][4 * rq + j] * invn1 + z1[j] * d1) * siluf(gt[j]);
;         uint2 ov; ov.x = pack2(yy[0], yy[1]); ov.y = pack2(yy[2], yy[3]);
;         *(uint2*)(dst + t4) = ov;
;       }
	v_and_b32_e32 v168, 0xffff0000, v100
	v_lshlrev_b32_e32 v169, 16, v101
	v_and_b32_e32 v170, 0xffff0000, v101
	v_lshlrev_b32_e32 v171, 16, v102
	v_and_b32_e32 v172, 0xffff0000, v102
	v_lshlrev_b32_e32 v173, 16, v103
	v_mul_f32_e32 v178, v83, v168
	v_fmac_f32_e32 v178, v82, v169
	v_fmac_f32_e32 v178, v80, v170
	v_add_f32_e32 v178, v70, v178
	v_mul_f32_e32 v179, v83, v169
	v_fmac_f32_e32 v179, v82, v170
	v_fmac_f32_e32 v179, v80, v171
	v_add_f32_e32 v179, v70, v179
	v_mul_f32_e32 v180, v83, v170
	v_fmac_f32_e32 v180, v82, v171
	v_fmac_f32_e32 v180, v80, v172
	v_add_f32_e32 v180, v70, v180
	v_mul_f32_e32 v181, v83, v171
	v_fmac_f32_e32 v181, v82, v172
	v_fmac_f32_e32 v181, v80, v173
	v_add_f32_e32 v181, v70, v181
	v_lshlrev_b32_e32 v174, 16, v164
	v_and_b32_e32 v175, 0xffff0000, v164
	v_lshlrev_b32_e32 v176, 16, v165
	v_and_b32_e32 v177, 0xffff0000, v165
	v_mul_f32_e32 v174, v68, v174
	v_mul_f32_e32 v175, v68, v175
	v_mul_f32_e32 v176, v68, v176
	v_mul_f32_e32 v177, v68, v177
	v_fmac_f32_e32 v174, v238, v8
	v_fmac_f32_e32 v175, v238, v9
	v_fmac_f32_e32 v176, v238, v10
	v_fmac_f32_e32 v177, v238, v11
	v_mul_f32_e32 v174, v178, v174
	v_mul_f32_e32 v175, v179, v175
	v_mul_f32_e32 v176, v180, v176
	v_mul_f32_e32 v177, v181, v177
	v_lshlrev_b32_e32 v168, 16, v104
	v_and_b32_e32 v169, 0xffff0000, v104
	v_lshlrev_b32_e32 v170, 16, v105
	v_and_b32_e32 v171, 0xffff0000, v105
	v_mul_f32_e32 v178, 0xbfb8aa3b, v168
	v_mul_f32_e32 v179, 0xbfb8aa3b, v169
	v_mul_f32_e32 v180, 0xbfb8aa3b, v170
	v_mul_f32_e32 v181, 0xbfb8aa3b, v171
	v_exp_f32_e32 v178, v178
	v_exp_f32_e32 v179, v179
	v_exp_f32_e32 v180, v180
	v_exp_f32_e32 v181, v181
	v_add_f32_e32 v178, 1.0, v178
	v_add_f32_e32 v179, 1.0, v179
	v_add_f32_e32 v180, 1.0, v180
	v_add_f32_e32 v181, 1.0, v181
	v_rcp_f32_e32 v178, v178
	v_rcp_f32_e32 v179, v179
	v_rcp_f32_e32 v180, v180
	v_rcp_f32_e32 v181, v181
	v_mul_f32_e32 v178, v178, v168
	v_mul_f32_e32 v179, v179, v169
	v_mul_f32_e32 v180, v180, v170
	v_mul_f32_e32 v181, v181, v171
	v_mul_f32_e32 v174, v174, v178
	v_mul_f32_e32 v175, v175, v179
	v_mul_f32_e32 v176, v176, v180
	v_mul_f32_e32 v177, v177, v181
	v_cvt_pk_bf16_f32 v182, v174, v175
	v_cvt_pk_bf16_f32 v183, v176, v177
	global_store_dwordx2 v234, v[182:183], s[6:7] offset:224
	v_cmp_ne_u32_e32 vcc, 0x1f84, v233
	s_nop 1
	v_and_b32_e32 v168, 0xffff0000, v106
	v_lshlrev_b32_e32 v169, 16, v107
	v_and_b32_e32 v170, 0xffff0000, v107
	v_lshlrev_b32_e32 v171, 16, v108
	v_and_b32_e32 v172, 0xffff0000, v108
	v_lshlrev_b32_e32 v173, 16, v109
	v_cndmask_b32_e32 v173, 0, v173, vcc
	v_mul_f32_e32 v178, v83, v168
	v_fmac_f32_e32 v178, v82, v169
	v_fmac_f32_e32 v178, v80, v170
	v_add_f32_e32 v178, v70, v178
	v_mul_f32_e32 v179, v83, v169
	v_fmac_f32_e32 v179, v82, v170
	v_fmac_f32_e32 v179, v80, v171
	v_add_f32_e32 v179, v70, v179
	v_mul_f32_e32 v180, v83, v170
	v_fmac_f32_e32 v180, v82, v171
	v_fmac_f32_e32 v180, v80, v172
	v_add_f32_e32 v180, v70, v180
	v_mul_f32_e32 v181, v83, v171
	v_fmac_f32_e32 v181, v82, v172
	v_fmac_f32_e32 v181, v80, v173
	v_add_f32_e32 v181, v70, v181
	v_lshlrev_b32_e32 v174, 16, v166
	v_and_b32_e32 v175, 0xffff0000, v166
	v_lshlrev_b32_e32 v176, 16, v167
	v_and_b32_e32 v177, 0xffff0000, v167
	v_mul_f32_e32 v174, v68, v174
	v_mul_f32_e32 v175, v68, v175
	v_mul_f32_e32 v176, v68, v176
	v_mul_f32_e32 v177, v68, v177
	v_fmac_f32_e32 v174, v238, v12
	v_fmac_f32_e32 v175, v238, v13
	v_fmac_f32_e32 v176, v238, v14
	v_fmac_f32_e32 v177, v238, v15
	v_mul_f32_e32 v174, v178, v174
	v_mul_f32_e32 v175, v179, v175
	v_mul_f32_e32 v176, v180, v176
	v_mul_f32_e32 v177, v181, v177
	v_lshlrev_b32_e32 v168, 16, v110
	v_and_b32_e32 v169, 0xffff0000, v110
	v_lshlrev_b32_e32 v170, 16, v111
	v_and_b32_e32 v171, 0xffff0000, v111
	v_mul_f32_e32 v178, 0xbfb8aa3b, v168
	v_mul_f32_e32 v179, 0xbfb8aa3b, v169
	v_mul_f32_e32 v180, 0xbfb8aa3b, v170
	v_mul_f32_e32 v181, 0xbfb8aa3b, v171
	v_exp_f32_e32 v178, v178
	v_exp_f32_e32 v179, v179
	v_exp_f32_e32 v180, v180
	v_exp_f32_e32 v181, v181
	v_add_f32_e32 v178, 1.0, v178
	v_add_f32_e32 v179, 1.0, v179
	v_add_f32_e32 v180, 1.0, v180
	v_add_f32_e32 v181, 1.0, v181
	v_rcp_f32_e32 v178, v178
	v_rcp_f32_e32 v179, v179
	v_rcp_f32_e32 v180, v180
	v_rcp_f32_e32 v181, v181
	v_mul_f32_e32 v178, v178, v168
	v_mul_f32_e32 v179, v179, v169
	v_mul_f32_e32 v180, v180, v170
	v_mul_f32_e32 v181, v181, v171
	v_mul_f32_e32 v174, v174, v178
	v_mul_f32_e32 v175, v175, v179
	v_mul_f32_e32 v176, v176, v180
	v_mul_f32_e32 v177, v177, v181
	v_cvt_pk_bf16_f32 v182, v174, v175
	v_cvt_pk_bf16_f32 v183, v176, v177
	global_store_dwordx2 v234, v[182:183], s[6:7] offset:240
	s_mov_b64 s[8:9], 0
